# adds: workgroups whose first attention item was one of the 256 long ones leave the queue after it (no final counter round trip before the barrier)
# baseline (speedup 1.0000x reference)
.Ldq_shared:
	v_readlane_b32 vcc_lo, v251, 0
	s_nop 3
	s_cmp_lt_u32 vcc_lo, 0x100
	s_cbranch_scc0 .Ldq_take
	v_mov_b32_e32 v4, 0x400
	s_branch .LBB0_78
